# v74 + attention max/sum cross-lane reductions via v_permlane16/32_swap instead of ds_bpermute
# baseline (speedup 1.0000x reference)
; #define LAS __attribute__((address_space(3)))
; __device__ __forceinline__ void attn_phase(const Params& p, LAS unsigned char* lds, int tid, int G, int bid) {
;     ...
;         float mx = -INFINITY;
; #pragma unroll
;         for (int tt = 0; tt < 10; ++tt)
; #pragma unroll
;             for (int j = 0; j < 4; ++j) { const int kj = 16 * (tstart + tt) + 4 * quad + j, delta = qi + 128 - kj;
;                 const bool valid = (delta >= 0) && (delta <= 128) && (nb > 0 || kj >= 128);
;                 const float v = valid ? s[tt][j] - sl2 * (float)delta : -INFINITY; s[tt][j] = v; mx = fmaxf(mx, v); }
;         mx = fmaxf(mx, __shfl_xor(mx, 16)); mx = fmaxf(mx, __shfl_xor(mx, 32));
;         float den = 0.f;
; #pragma unroll
;         for (int tt = 0; tt < 10; ++tt)
; #pragma unroll
;             for (int j = 0; j < 4; ++j) { const float e = __builtin_amdgcn_exp2f(s[tt][j] - mx); s[tt][j] = e; den += e; }
;         den += __shfl_xor(den, 16); den += __shfl_xor(den, 32);
;         f32x4 o[4];
; #pragma unroll
;         for (int dt = 0; dt < 4; ++dt) o[dt] = (f32x4){0.f, 0.f, 0.f, 0.f};
; #pragma unroll
;         for (int c = 0; c < 5; ++c) {
;             int p0_ = 0, p1_ = 0;
;             p0_ = __builtin_amdgcn_cvt_pk_fp8_f32(s[2 * c][0], s[2 * c][1], p0_, false); p0_ = __builtin_amdgcn_cvt_pk_fp8_f32(s[2 * c][2], s[2 * c][3], p0_, true);
;             p1_ = __builtin_amdgcn_cvt_pk_fp8_f32(s[2 * c + 1][0], s[2 * c + 1][1], p1_, false); p1_ = __builtin_amdgcn_cvt_pk_fp8_f32(s[2 * c + 1][2], s[2 * c + 1][3], p1_, true);
;             const long pf = (long)(((unsigned long long)(unsigned)p1_ << 32) | (unsigned long long)(unsigned)p0_);
; #pragma unroll
;             for (int dt = 0; dt < 4; ++dt) { const LAS unsigned char* vp = lds + VT_OFF + (16 * dt + fr) * VT_PITCH + 16 * (tstart + 2 * c) + 4 * quad;
;                 const unsigned lo = *(const LAS unsigned*)vp, hi = *(const LAS unsigned*)(vp + 16);
;                 const long vf = (long)(((unsigned long long)hi << 32) | (unsigned long long)lo);
;                 o[dt] = __builtin_amdgcn_mfma_f32_16x16x32_fp8_fp8(vf, pf, o[dt], 0, 0, 0); }
.Lattn_nb_ok:
	s_mov_b32 s12, 0xff800000
	v_max3_f32 v118, v62, s12, v63
	v_max3_f32 v118, v118, v116, v117
	v_max3_f32 v118, v118, v114, v115
	v_max3_f32 v118, v118, v112, v113
	v_max3_f32 v118, v118, v110, v111
	v_max3_f32 v118, v118, v108, v109
	v_max3_f32 v118, v118, v106, v107
	v_max3_f32 v118, v118, v104, v105
	v_max3_f32 v118, v118, v82, v83
	v_max3_f32 v118, v118, v80, v81
	v_max3_f32 v118, v118, v78, v79
	v_max3_f32 v118, v118, v76, v77
	v_max3_f32 v118, v118, v74, v75
	v_max3_f32 v118, v118, v72, v73
	v_max3_f32 v118, v118, v70, v71
	v_max3_f32 v118, v118, v68, v69
	v_max3_f32 v118, v118, v66, v67
	v_max3_f32 v118, v118, v64, v65
	v_max3_f32 v118, v118, v60, v61
	v_max3_f32 v9, v118, v10, v11
	v_mov_b32_e32 v118, v9
	v_mov_b32_e32 v213, v9
	s_nop 1
	v_permlane16_swap_b32_e32 v118, v213
	v_max_f32_e32 v9, v118, v213
	v_mov_b32_e32 v118, v9
	v_mov_b32_e32 v213, v9
	s_nop 1
	v_permlane32_swap_b32_e32 v118, v213
	v_max_f32_e32 v9, v118, v213
	v_sub_f32_e32 v62, v62, v9
	v_exp_f32_e32 v62, v62
	v_sub_f32_e32 v63, v63, v9
	v_exp_f32_e32 v63, v63
	v_sub_f32_e32 v116, v116, v9
	v_exp_f32_e32 v116, v116
	v_sub_f32_e32 v117, v117, v9
	v_exp_f32_e32 v117, v117
	v_sub_f32_e32 v114, v114, v9
	v_add_f32_e32 v118, 0, v62
	v_exp_f32_e32 v114, v114
	v_sub_f32_e32 v115, v115, v9
	v_add_f32_e32 v118, v63, v118
	v_exp_f32_e32 v115, v115
	v_sub_f32_e32 v112, v112, v9
	v_add_f32_e32 v118, v116, v118
	v_exp_f32_e32 v112, v112
	v_sub_f32_e32 v113, v113, v9
	v_add_f32_e32 v118, v117, v118
	v_exp_f32_e32 v113, v113
	v_sub_f32_e32 v110, v110, v9
	v_add_f32_e32 v118, v114, v118
	v_exp_f32_e32 v110, v110
	v_sub_f32_e32 v111, v111, v9
	v_add_f32_e32 v118, v115, v118
	v_exp_f32_e32 v111, v111
	v_sub_f32_e32 v108, v108, v9
	v_add_f32_e32 v118, v112, v118
	v_exp_f32_e32 v108, v108
	v_sub_f32_e32 v109, v109, v9
	v_add_f32_e32 v118, v113, v118
	v_exp_f32_e32 v109, v109
	v_sub_f32_e32 v106, v106, v9
	v_add_f32_e32 v118, v110, v118
	v_exp_f32_e32 v106, v106
	v_sub_f32_e32 v107, v107, v9
	v_add_f32_e32 v118, v111, v118
	v_exp_f32_e32 v107, v107
	v_sub_f32_e32 v104, v104, v9
	v_add_f32_e32 v118, v108, v118
	v_exp_f32_e32 v104, v104
	v_sub_f32_e32 v105, v105, v9
	v_add_f32_e32 v118, v109, v118
	v_exp_f32_e32 v105, v105
	v_sub_f32_e32 v82, v82, v9
	v_add_f32_e32 v118, v106, v118
	v_exp_f32_e32 v82, v82
	v_sub_f32_e32 v83, v83, v9
	v_add_f32_e32 v118, v107, v118
	v_exp_f32_e32 v83, v83
	v_sub_f32_e32 v80, v80, v9
	v_add_f32_e32 v118, v104, v118
	v_exp_f32_e32 v80, v80
	v_sub_f32_e32 v81, v81, v9
	v_add_f32_e32 v118, v105, v118
	v_exp_f32_e32 v81, v81
	v_sub_f32_e32 v78, v78, v9
	v_add_f32_e32 v118, v82, v118
	v_exp_f32_e32 v78, v78
	v_sub_f32_e32 v79, v79, v9
	v_add_f32_e32 v118, v83, v118
	v_exp_f32_e32 v79, v79
	v_sub_f32_e32 v76, v76, v9
	v_add_f32_e32 v118, v80, v118
	v_exp_f32_e32 v119, v76
	v_add_f32_e32 v118, v81, v118
	v_add_f32_e32 v118, v78, v118
	v_add_f32_e32 v118, v79, v118
	v_sub_f32_e32 v77, v77, v9
	v_add_f32_e32 v76, v119, v118
	v_exp_f32_e32 v118, v77
	v_sub_f32_e32 v74, v74, v9
	v_exp_f32_e32 v186, v74
	v_sub_f32_e32 v75, v75, v9
	v_exp_f32_e32 v187, v75
	v_sub_f32_e32 v72, v72, v9
	v_exp_f32_e32 v188, v72
	v_sub_f32_e32 v73, v73, v9
	v_add_f32_e32 v76, v118, v76
	v_exp_f32_e32 v189, v73
	v_sub_f32_e32 v70, v70, v9
	v_add_f32_e32 v74, v186, v76
	v_exp_f32_e32 v190, v70
	v_sub_f32_e32 v71, v71, v9
	v_add_f32_e32 v74, v187, v74
	v_exp_f32_e32 v191, v71
	v_sub_f32_e32 v68, v68, v9
	v_add_f32_e32 v72, v188, v74
	v_exp_f32_e32 v192, v68
	v_sub_f32_e32 v69, v69, v9
	v_add_f32_e32 v72, v189, v72
	v_exp_f32_e32 v193, v69
	v_sub_f32_e32 v66, v66, v9
	v_add_f32_e32 v70, v190, v72
	v_exp_f32_e32 v194, v66
	v_sub_f32_e32 v67, v67, v9
	v_add_f32_e32 v70, v191, v70
	v_exp_f32_e32 v195, v67
	v_sub_f32_e32 v64, v64, v9
	v_add_f32_e32 v68, v192, v70
	v_exp_f32_e32 v196, v64
	v_sub_f32_e32 v65, v65, v9
	v_add_f32_e32 v68, v193, v68
	v_exp_f32_e32 v197, v65
	v_sub_f32_e32 v60, v60, v9
	v_add_f32_e32 v66, v194, v68
	v_exp_f32_e32 v198, v60
	v_sub_f32_e32 v61, v61, v9
	v_add_f32_e32 v66, v195, v66
	v_exp_f32_e32 v199, v61
	v_sub_f32_e32 v10, v10, v9
	v_add_f32_e32 v64, v196, v66
	v_exp_f32_e32 v200, v10
	v_sub_f32_e32 v11, v11, v9
	v_add_f32_e32 v64, v197, v64
	v_exp_f32_e32 v201, v11
	v_add_f32_e32 v60, v198, v64
	v_add_f32_e32 v60, v199, v60
	v_add_f32_e32 v10, v200, v60
	v_add_f32_e32 v10, v201, v10
	v_mov_b32_e32 v11, v10
	v_mov_b32_e32 v213, v10
	s_nop 1
	v_permlane16_swap_b32_e32 v11, v213
	v_add_f32_e32 v202, v11, v213
	v_cvt_pk_fp8_f32 v11, v114, v115
	v_cvt_pk_fp8_f32 v11, v112, v113 op_sel:[0,0,1]
	ds_read_b64_tr_b8 v[60:61], v246 offset:0
	ds_read_b64_tr_b8 v[64:65], v246 offset:16
	ds_read_b64_tr_b8 v[68:69], v246 offset:32
	ds_read_b64_tr_b8 v[72:73], v246 offset:48
	ds_read_b64_tr_b8 v[214:215], v246 offset:2560
	ds_read_b64_tr_b8 v[216:217], v246 offset:2576
	ds_read_b64_tr_b8 v[218:219], v246 offset:2592
	ds_read_b64_tr_b8 v[220:221], v246 offset:2608
	ds_read_b64_tr_b8 v[222:223], v246 offset:5120
	ds_read_b64_tr_b8 v[224:225], v246 offset:5136
	ds_read_b64_tr_b8 v[226:227], v246 offset:5152
	ds_read_b64_tr_b8 v[228:229], v246 offset:5168
	v_cvt_pk_fp8_f32 v10, v62, v63
	v_mov_b32_e32 v203, v202
	v_mov_b32_e32 v213, v202
	s_nop 1
	v_permlane32_swap_b32_e32 v203, v213
	v_add_f32_e32 v203, v203, v213
	v_cvt_pk_fp8_f32 v10, v116, v117 op_sel:[0,0,1]
	s_waitcnt lgkmcnt(8)
; #define LAS __attribute__((address_space(3)))
; __device__ __forceinline__ float f8c(float v) { return fminf(fmaxf(v, -448.f), 448.f); }
; #define LDS_WAIT() asm volatile("s_waitcnt lgkmcnt(0)" ::: "memory")
; __device__ __forceinline__ void attn_phase(const Params& p, LAS unsigned char* lds, int tid, int G, int bid) {
;     ...
;         for (int c = 0; c < 5; ++c) {
;             int p0_ = 0, p1_ = 0;
;             p0_ = __builtin_amdgcn_cvt_pk_fp8_f32(s[2 * c][0], s[2 * c][1], p0_, false); p0_ = __builtin_amdgcn_cvt_pk_fp8_f32(s[2 * c][2], s[2 * c][3], p0_, true);
;             p1_ = __builtin_amdgcn_cvt_pk_fp8_f32(s[2 * c + 1][0], s[2 * c + 1][1], p1_, false); p1_ = __builtin_amdgcn_cvt_pk_fp8_f32(s[2 * c + 1][2], s[2 * c + 1][3], p1_, true);
;             const long pf = (long)(((unsigned long long)(unsigned)p1_ << 32) | (unsigned long long)(unsigned)p0_);
; #pragma unroll
;             for (int dt = 0; dt < 4; ++dt) { const LAS unsigned char* vp = lds + VT_OFF + (16 * dt + fr) * VT_PITCH + 16 * (tstart + 2 * c) + 4 * quad;
;                 const unsigned lo = *(const LAS unsigned*)vp, hi = *(const LAS unsigned*)(vp + 16);
;                 const long vf = (long)(((unsigned long long)hi << 32) | (unsigned long long)lo);
;                 o[dt] = __builtin_amdgcn_mfma_f32_16x16x32_fp8_fp8(vf, pf, o[dt], 0, 0, 0); }
;         }
;         const float inv = 1.0f / den;
;         { LAS unsigned char* ost = lds + OST_OFF + w * 2304;
; #pragma unroll
;           for (int dt = 0; dt < 4; ++dt) { int wv = 0; wv = __builtin_amdgcn_cvt_pk_fp8_f32(f8c(o[dt][0] * inv), f8c(o[dt][1] * inv), wv, false); wv = __builtin_amdgcn_cvt_pk_fp8_f32(f8c(o[dt][2] * inv), f8c(o[dt][3] * inv), wv, true);
;               *(LAS unsigned*)(ost + fr * 80 + 16 * dt + 4 * quad) = (unsigned)wv; }
;           LDS_WAIT();
;           const int q2 = lane >> 2, ck = lane & 3, tq2 = ((nb * 128 + 16 * w + q2) << dsh) + r;
;           const u32x4 r0 = *(const LAS u32x4*)(ost + q2 * 80 + ck * 16);
;           unsigned char* op = (unsigned char*)OG + ((size_t)g * M + (size_t)b * SEQ + tq2) * AOW + hh * 64 + ck * 16;
;           *(u32x4*)op = r0; }
;         if (quad == 0) LSE[(size_t)uid * 128 + qi] = (mx + __builtin_amdgcn_logf(den)) * LN2F;
	s_nop 0
	v_mfma_f32_16x16x32_fp8_fp8 v[60:63], v[60:61], v[10:11], 0
	v_mfma_f32_16x16x32_fp8_fp8 v[64:67], v[64:65], v[10:11], 0
	v_mfma_f32_16x16x32_fp8_fp8 v[68:71], v[68:69], v[10:11], 0
	v_mfma_f32_16x16x32_fp8_fp8 v[72:75], v[72:73], v[10:11], 0
	ds_read_b64_tr_b8 v[230:231], v246 offset:7680
	ds_read_b64_tr_b8 v[232:233], v246 offset:7696
	ds_read_b64_tr_b8 v[234:235], v246 offset:7712
	ds_read_b64_tr_b8 v[236:237], v246 offset:7728
	v_cvt_pk_fp8_f32 v10, v110, v111
	v_cvt_pk_fp8_f32 v11, v106, v107
	v_cvt_pk_fp8_f32 v10, v108, v109 op_sel:[0,0,1]
	v_cvt_pk_fp8_f32 v11, v104, v105 op_sel:[0,0,1]
	s_waitcnt lgkmcnt(8)
	s_nop 0
	v_mfma_f32_16x16x32_fp8_fp8 v[60:63], v[214:215], v[10:11], v[60:63]
	v_mfma_f32_16x16x32_fp8_fp8 v[64:67], v[216:217], v[10:11], v[64:67]
	v_mfma_f32_16x16x32_fp8_fp8 v[68:71], v[218:219], v[10:11], v[68:71]
	v_mfma_f32_16x16x32_fp8_fp8 v[72:75], v[220:221], v[10:11], v[72:75]
	ds_read_b64_tr_b8 v[238:239], v246 offset:10240
	ds_read_b64_tr_b8 v[240:241], v246 offset:10256
	ds_read_b64_tr_b8 v[242:243], v246 offset:10272
	ds_read_b64_tr_b8 v[244:245], v246 offset:10288
	v_cvt_pk_fp8_f32 v10, v82, v83
	v_cvt_pk_fp8_f32 v11, v78, v79
	v_cvt_pk_fp8_f32 v10, v80, v81 op_sel:[0,0,1]
	v_cvt_pk_fp8_f32 v11, v119, v118 op_sel:[0,0,1]
	s_waitcnt lgkmcnt(8)
	s_nop 0
	v_mfma_f32_16x16x32_fp8_fp8 v[60:63], v[222:223], v[10:11], v[60:63]
	v_mfma_f32_16x16x32_fp8_fp8 v[64:67], v[224:225], v[10:11], v[64:67]
	v_mfma_f32_16x16x32_fp8_fp8 v[68:71], v[226:227], v[10:11], v[68:71]
	v_mfma_f32_16x16x32_fp8_fp8 v[72:75], v[228:229], v[10:11], v[72:75]
	v_cvt_pk_fp8_f32 v10, v186, v187
	v_cvt_pk_fp8_f32 v11, v190, v191
	v_cvt_pk_fp8_f32 v10, v188, v189 op_sel:[0,0,1]
	v_cvt_pk_fp8_f32 v11, v192, v193 op_sel:[0,0,1]
	s_waitcnt lgkmcnt(4)
	s_nop 0
	v_mfma_f32_16x16x32_fp8_fp8 v[60:63], v[230:231], v[10:11], v[60:63]
	v_mfma_f32_16x16x32_fp8_fp8 v[64:67], v[232:233], v[10:11], v[64:67]
	v_mfma_f32_16x16x32_fp8_fp8 v[68:71], v[234:235], v[10:11], v[68:71]
	v_mfma_f32_16x16x32_fp8_fp8 v[72:75], v[236:237], v[10:11], v[72:75]
	v_cvt_pk_fp8_f32 v10, v194, v195
	v_cvt_pk_fp8_f32 v11, v198, v199
	v_cvt_pk_fp8_f32 v10, v196, v197 op_sel:[0,0,1]
	v_cvt_pk_fp8_f32 v11, v200, v201 op_sel:[0,0,1]
	s_waitcnt lgkmcnt(0)
	s_nop 0
	v_mfma_f32_16x16x32_fp8_fp8 v[60:63], v[238:239], v[10:11], v[60:63]
	v_mfma_f32_16x16x32_fp8_fp8 v[76:79], v[240:241], v[10:11], v[64:67]
	v_mfma_f32_16x16x32_fp8_fp8 v[214:217], v[242:243], v[10:11], v[68:71]
	v_mfma_f32_16x16x32_fp8_fp8 v[218:221], v[244:245], v[10:11], v[72:75]
	v_mov_b32_e32 v64, v203
	v_div_scale_f32 v10, s[6:7], v64, v64, 1.0
	v_rcp_f32_e32 v11, v10
	s_nop 0
	v_fma_f32 v65, -v10, v11, 1.0
	v_fmac_f32_e32 v11, v65, v11
	v_div_scale_f32 v65, vcc, 1.0, v64, 1.0
	v_mul_f32_e32 v74, v65, v11
	v_fma_f32 v75, -v10, v74, v65
	v_fmac_f32_e32 v74, v75, v11
	v_fma_f32 v10, -v10, v74, v65
	v_div_fmas_f32 v10, v10, v11, v74
	v_div_fixup_f32 v10, v10, v64, 1.0
	v_mul_f32_e32 v11, v10, v60
	v_mul_f32_e32 v60, v10, v61
	v_med3_f32 v11, v11, s81, v185
	v_med3_f32 v60, v60, s81, v185
	v_cvt_pk_fp8_f32 v61, v11, v60
	v_mul_f32_e32 v11, v10, v62
	v_mul_f32_e32 v60, v10, v63
	v_med3_f32 v11, v11, s81, v185
	v_med3_f32 v60, v60, s81, v185
	v_cvt_pk_fp8_f32 v61, v11, v60 op_sel:[0,0,1]
	v_mul_f32_e32 v11, v10, v76
	v_mul_f32_e32 v60, v10, v77
	v_med3_f32 v11, v11, s81, v185
	v_med3_f32 v60, v60, s81, v185
	v_cvt_pk_fp8_f32 v62, v11, v60
	v_mul_f32_e32 v11, v10, v78
	v_mul_f32_e32 v60, v10, v79
	v_med3_f32 v11, v11, s81, v185
	v_med3_f32 v60, v60, s81, v185
	v_cvt_pk_fp8_f32 v62, v11, v60 op_sel:[0,0,1]
	v_mul_f32_e32 v11, v10, v214
	v_mul_f32_e32 v60, v10, v215
	v_med3_f32 v11, v11, s81, v185
	ds_write2_b32 v181, v61, v62 offset1:4
	v_med3_f32 v60, v60, s81, v185
	v_cvt_pk_fp8_f32 v61, v11, v60
	v_mul_f32_e32 v11, v10, v216
	v_mul_f32_e32 v60, v10, v217
	v_med3_f32 v11, v11, s81, v185
	v_med3_f32 v60, v60, s81, v185
	v_cvt_pk_fp8_f32 v61, v11, v60 op_sel:[0,0,1]
	v_mul_f32_e32 v11, v10, v218
	v_mul_f32_e32 v60, v10, v219
	v_med3_f32 v11, v11, s81, v185
	v_med3_f32 v60, v60, s81, v185
	v_cvt_pk_fp8_f32 v62, v11, v60
	v_mul_f32_e32 v11, v10, v220
	v_mul_f32_e32 v10, v10, v221
	v_med3_f32 v11, v11, s81, v185
	v_med3_f32 v10, v10, s81, v185
	v_cvt_pk_fp8_f32 v62, v11, v10 op_sel:[0,0,1]
	v_lshl_add_u32 v10, s86, 7, v124
	v_lshlrev_b32_e32 v10, s1, v10
	v_add_u32_e32 v10, s5, v10
	s_ashr_i32 s5, s4, 31
	s_ashr_i32 s1, s0, 31
	s_lshl_b64 s[4:5], s[4:5], 15
	s_lshl_b64 s[0:1], s[0:1], 11
	ds_write2_b32 v181, v61, v62 offset0:8 offset1:12
	s_add_u32 s0, s4, s0
	s_waitcnt lgkmcnt(0)
	s_addc_u32 s1, s5, s1
	v_ashrrev_i32_e32 v11, 31, v10
	ds_read_b128 v[60:63], v182
	v_lshl_add_u64 v[10:11], s[0:1], 0, v[10:11]
	v_lshlrev_b64 v[10:11], 8, v[10:11]
	v_lshl_add_u64 v[10:11], s[94:95], 0, v[10:11]
	s_lshl_b32 s86, s11, 6
	v_lshl_add_u64 v[10:11], v[10:11], 0, s[86:87]
	v_lshl_add_u64 v[10:11], v[10:11], 0, v[84:85]
	s_waitcnt lgkmcnt(0)
	global_store_dwordx4 v[10:11], v[60:63], off
	s_mov_b64 s[0:1], exec
	v_readlane_b32 s4, v250, 35
	v_readlane_b32 s5, v250, 36
	s_and_b64 s[4:5], s[0:1], s[4:5]
	s_mov_b64 exec, s[4:5]
	s_cbranch_execz .LBB0_286
	v_log_f32_e32 v10, v64
	s_nop 0
	v_add_f32_e32 v9, v9, v10
	v_mul_f32_e32 v9, 0x3f317218, v9
	global_store_dword v[98:99], v9, off
